# SSD prompt unit: batched LDS reads for the C.H MFMA chains and the transposed reads, counted prefetch wait (on v22)
# speedup vs baseline: 1.0110x; 1.0008x over previous
.LBB0_368:
	v_add_u32_e32 v218, v128, v132
	ds_read_b128 v[74:77], v218
	ds_read_b128 v[220:223], v203
	ds_read_b128 v[78:81], v218 offset:64
	ds_read_b128 v[224:227], v203 offset:64
	ds_read_b128 v[228:231], v218 offset:128
	ds_read_b128 v[232:235], v203 offset:128
	ds_read_b128 v[236:239], v218 offset:192
	s_waitcnt lgkmcnt(6)
	v_mfma_f32_16x16x32_bf16 v[74:77], v[66:69], v[74:77], 0
	s_waitcnt lgkmcnt(5)
	v_mfma_f32_16x16x32_bf16 v[220:223], v[66:69], v[220:223], 0
	ds_read_b128 v[66:69], v203 offset:192
	s_waitcnt lgkmcnt(5)
	v_mfma_f32_16x16x32_bf16 v[74:77], v[62:65], v[78:81], v[74:77]
	s_waitcnt lgkmcnt(4)
	v_mfma_f32_16x16x32_bf16 v[220:223], v[62:65], v[224:227], v[220:223]
	s_waitcnt lgkmcnt(3)
	v_mfma_f32_16x16x32_bf16 v[74:77], v[58:61], v[228:231], v[74:77]
	s_waitcnt lgkmcnt(2)
	v_mfma_f32_16x16x32_bf16 v[220:223], v[58:61], v[232:235], v[220:223]
	s_waitcnt lgkmcnt(1)
	v_mfma_f32_16x16x32_bf16 v[74:77], v[70:73], v[236:239], v[74:77]
	s_waitcnt lgkmcnt(0)
	v_mfma_f32_16x16x32_bf16 v[58:61], v[70:73], v[66:69], v[220:223]
	s_waitcnt vmcnt(9)
	v_and_b32_e32 v63, 64, v204
	v_xor_b32_e32 v62, 1, v204
	v_add_u32_e32 v63, 64, v63
	v_cmp_lt_i32_e32 vcc, v62, v63
	s_nop 1
	v_cndmask_b32_e32 v62, v204, v62, vcc
	v_lshlrev_b32_e32 v64, 2, v62
	v_xor_b32_e32 v62, 2, v204
	v_cmp_lt_i32_e32 vcc, v62, v63
	s_nop 1
	v_cndmask_b32_e32 v62, v204, v62, vcc
	v_lshlrev_b32_e32 v66, 2, v62
	v_xor_b32_e32 v62, 4, v204
	v_cmp_lt_i32_e32 vcc, v62, v63
	s_nop 1
	v_cndmask_b32_e32 v62, v204, v62, vcc
	v_lshlrev_b32_e32 v67, 2, v62
	v_xor_b32_e32 v62, 8, v204
	v_cmp_lt_i32_e32 vcc, v62, v63
	s_nop 1
	v_cndmask_b32_e32 v62, v204, v62, vcc
	v_lshlrev_b32_e32 v65, 2, v62
	ds_read_b32 v62, v166
	ds_read_u16 v68, v167
	ds_read_u16 v73, v167 offset:32
	s_waitcnt lgkmcnt(2)
	v_mul_f32_e32 v62, 0x3fb8aa3b, v62
	v_exp_f32_e32 v72, v62
	s_waitcnt lgkmcnt(1)
	v_lshlrev_b32_e32 v68, 16, v68
	v_add_u32_e32 v62, -3, v118
	v_ashrrev_i32_e32 v63, 31, v62
	v_fma_f32 v54, v74, v72, v54
	v_fmac_f32_e32 v54, v208, v68
	v_lshlrev_b32_e32 v68, 16, v217
	v_mul_f32_e32 v69, 0xbfb8aa3b, v68
	v_exp_f32_e32 v69, v69
	v_fma_f32 v50, v58, v72, v50
	v_lshlrev_b32_e32 v58, 16, v216
	v_add_f32_e32 v69, 1.0, v69
	v_rcp_f32_e32 v69, v69
	s_nop 0
	v_mul_f32_e32 v68, v69, v68
	v_mul_f32_e32 v54, v68, v54
	v_lshlrev_b64 v[68:69], 12, v[62:63]
	v_lshl_or_b32 v68, s94, 1, v68
	v_cvt_pk_bf16_f32 v74, v54, s0
	v_lshl_add_u64 v[70:71], v[98:99], 0, v[68:69]
	global_store_short v[70:71], v74, off
	s_waitcnt lgkmcnt(0)
	v_lshlrev_b32_e32 v70, 16, v73
	v_fmac_f32_e32 v50, v208, v70
	v_mul_f32_e32 v70, 0xbfb8aa3b, v58
	v_exp_f32_e32 v70, v70
	v_lshl_add_u64 v[68:69], v[116:117], 0, v[68:69]
	v_add_f32_e32 v70, 1.0, v70
	v_rcp_f32_e32 v70, v70
	s_nop 0
	v_mul_f32_e32 v58, v70, v58
	v_mul_f32_e32 v50, v58, v50
	v_mul_f32_e32 v58, v50, v50
	v_fmac_f32_e32 v58, v54, v54
	v_cvt_pk_bf16_f32 v50, v50, s0
	global_store_short v[68:69], v50, off
	ds_bpermute_b32 v50, v64, v58
	s_waitcnt lgkmcnt(0)
	v_add_f32_e32 v50, v58, v50
	ds_bpermute_b32 v54, v66, v50
	s_waitcnt lgkmcnt(0)
	v_add_f32_e32 v50, v50, v54
	ds_bpermute_b32 v54, v67, v50
	s_waitcnt lgkmcnt(0)
	v_add_f32_e32 v50, v50, v54
	ds_bpermute_b32 v54, v65, v50
	s_and_saveexec_b64 s[24:25], s[4:5]
	s_cbranch_execz .LBB0_370
	v_lshlrev_b64 v[62:63], 8, v[62:63]
	s_waitcnt lgkmcnt(0)
	v_add_f32_e32 v50, v50, v54
	v_lshl_add_u64 v[62:63], s[88:89], 0, v[62:63]
	global_store_dword v[62:63], v50, off
